# v13 + final LayerNorm: g/b preloaded once into registers, per-row serialized load/wait/store chain removed
# speedup vs baseline: 1.0086x; 1.0037x over previous
; __device__ __forceinline__ void ln_row(const float* xin, float* yout, bf16_t* ybf, const float* g, const float* b, int lane) {
;     const f32x4* xr = (const f32x4*)xin + lane;
;     f32x4 v[8]; float s = 0.f;
; #pragma unroll
;     for (int j = 0; j < 8; ++j) { v[j] = xr[64 * j]; s += (v[j][0] + v[j][1]) + (v[j][2] + v[j][3]); }
;     const float mean = wave_sum(s, lane) * (1.f / DM); float s2 = 0.f;
; __global__ void __launch_bounds__(NWAVES * 64, 2) mega_fwd(Params P) {
;     ...
;     { PH_IDS
;       for (int m = gw; m < TOK; m += NGW) ln_row(H + (size_t)m * DM, H + (size_t)m * DM, (bf16_t*)nullptr, P.in[21] + (NLAYER - 1) * DM, P.in[22] + (NLAYER - 1) * DM, lane); }
.LBB0_1296:
	v_readlane_b32 s0, v255, 8
	v_readlane_b32 s1, v255, 9
	s_and_b64 vcc, exec, s[0:1]
	v_mbcnt_lo_u32_b32 v0, -1, 0
	v_mbcnt_hi_u32_b32 v0, -1, v0
	s_cbranch_vccnz .LBB0_1299
	v_ashrrev_i32_e32 v1, 31, v0
	v_lshlrev_b32_e32 v2, 2, v0
	v_lshlrev_b64 v[0:1], 4, v[0:1]
	v_xor_b32_e32 v56, 4, v2
	v_xor_b32_e32 v57, 8, v2
	v_xor_b32_e32 v58, 16, v2
	v_xor_b32_e32 v59, 32, v2
	v_xor_b32_e32 v60, 64, v2
	v_xor_b32_e32 v61, 0x80, v2
	v_lshl_add_u64 v[2:3], s[90:91], 0, v[0:1]
	s_mov_b64 s[0:1], 0x2000
	v_lshl_add_u64 v[4:5], s[92:93], 0, v[0:1]
	v_lshl_add_u64 v[32:33], v[2:3], 0, s[0:1]
	v_lshl_add_u64 v[34:35], v[4:5], 0, s[0:1]
	s_mov_b64 s[0:1], 0x3000
	v_lshl_add_u64 v[36:37], v[2:3], 0, s[0:1]
	v_lshl_add_u64 v[38:39], v[4:5], 0, s[0:1]
	s_mov_b64 s[0:1], 0x3400
	v_lshl_add_u64 v[40:41], v[2:3], 0, s[0:1]
	v_lshl_add_u64 v[42:43], v[4:5], 0, s[0:1]
	s_mov_b64 s[0:1], 0x3800
	v_lshl_add_u64 v[44:45], v[2:3], 0, s[0:1]
	v_lshl_add_u64 v[46:47], v[4:5], 0, s[0:1]
	s_mov_b64 s[0:1], 0x3c00
	v_lshl_add_u64 v[48:49], v[2:3], 0, s[0:1]
	v_lshl_add_u64 v[50:51], v[4:5], 0, s[0:1]
	s_add_i32 s4, s18, 0xfffff800
	s_lshl_b64 s[0:1], s[18:19], 13
	s_add_u32 s0, s94, s0
	s_addc_u32 s1, s95, s1
	v_lshl_add_u64 v[0:1], s[0:1], 0, v[0:1]
	s_mov_b64 s[0:1], 0x1c00
	v_lshl_add_u64 v[52:53], v[0:1], 0, s[0:1]
	v_mov_b32_e32 v62, 0x3727c5ac
	s_mov_b32 s5, 0xf800000
	v_mov_b32_e32 v63, 0x260
	s_mov_b64 s[2:3], 0x1000000
	global_load_dwordx4 v[100:103], v[32:33], off
	global_load_dwordx4 v[104:107], v[32:33], off offset:1024
	global_load_dwordx4 v[108:111], v[32:33], off offset:2048
	global_load_dwordx4 v[112:115], v[32:33], off offset:3072
	global_load_dwordx4 v[116:119], v[36:37], off
	global_load_dwordx4 v[120:123], v[40:41], off
	global_load_dwordx4 v[124:127], v[44:45], off
	global_load_dwordx4 v[128:131], v[48:49], off
	global_load_dwordx4 v[132:135], v[34:35], off
	global_load_dwordx4 v[136:139], v[34:35], off offset:1024
	global_load_dwordx4 v[140:143], v[34:35], off offset:2048
	global_load_dwordx4 v[144:147], v[34:35], off offset:3072
	global_load_dwordx4 v[148:151], v[38:39], off
	global_load_dwordx4 v[152:155], v[42:43], off
	global_load_dwordx4 v[156:159], v[46:47], off
	global_load_dwordx4 v[160:163], v[50:51], off
	s_waitcnt vmcnt(0)
.LBB0_1298:
	global_load_dwordx4 v[8:11], v[52:53], off offset:-3072
	global_load_dwordx4 v[12:15], v[52:53], off offset:-2048
	global_load_dwordx4 v[4:7], v[52:53], off offset:-1024
	v_add_co_u32_e32 v54, vcc, 0xfffff000, v52
	global_load_dwordx4 v[0:3], v[52:53], off
	s_nop 0
	v_addc_co_u32_e32 v55, vcc, -1, v53, vcc
	global_load_dwordx4 v[28:31], v[54:55], off offset:-3072
	global_load_dwordx4 v[24:27], v[54:55], off offset:-2048
	global_load_dwordx4 v[20:23], v[54:55], off offset:-1024
	global_load_dwordx4 v[16:19], v[52:53], off offset:-4096
	s_addk_i32 s4, 0x800
	s_cmpk_gt_i32 s4, 0x77ff
	s_waitcnt vmcnt(7)
	v_mov_b32_e32 v67, v10
	s_waitcnt vmcnt(6)
	v_mov_b32_e32 v70, v13
	v_mov_b32_e32 v71, v14
	v_mov_b32_e32 v72, v12
	v_mov_b32_e32 v73, v15
	s_waitcnt vmcnt(5)
	v_add_f32_e32 v74, v4, v5
	v_add_f32_e32 v76, v6, v7
	s_waitcnt vmcnt(4)
	v_mov_b32_e32 v75, v2
	v_mov_b32_e32 v77, v3
	v_pk_add_f32 v[70:71], v[70:71], v[72:73]
	v_pk_add_f32 v[72:73], v[74:75], v[76:77]
	s_waitcnt vmcnt(3)
	v_mov_b32_e32 v74, v28
	s_waitcnt vmcnt(2)
	v_mov_b32_e32 v75, v24
	v_mov_b32_e32 v76, v29
	v_mov_b32_e32 v77, v25
	v_mov_b32_e32 v78, v30
	v_mov_b32_e32 v79, v26
	v_mov_b32_e32 v80, v31
	v_mov_b32_e32 v81, v27
	v_mov_b32_e32 v69, v11
	s_waitcnt vmcnt(1)
	v_mov_b32_e32 v82, v21
	v_mov_b32_e32 v83, v22
	v_mov_b32_e32 v84, v20
	v_mov_b32_e32 v85, v23
	s_waitcnt vmcnt(0)
	v_add_f32_e32 v66, v16, v17
	v_add_f32_e32 v68, v18, v19
	v_pk_add_f32 v[74:75], v[74:75], v[76:77]
	v_pk_add_f32 v[76:77], v[78:79], v[80:81]
	v_pk_add_f32 v[78:79], v[82:83], v[84:85]
	v_pk_add_f32 v[66:67], v[66:67], v[68:69]
	v_pk_add_f32 v[68:69], v[74:75], v[76:77]
	v_pk_add_f32 v[74:75], v[78:79], v[78:79] op_sel:[0,1] op_sel_hi:[1,0]
	v_add_f32_e32 v64, 0, v68
	v_mov_b32_e32 v65, v8
	v_mov_b32_e32 v75, v9
	v_add_f32_e32 v64, v64, v69
	v_pk_add_f32 v[64:65], v[64:65], v[74:75]
	v_pk_add_f32 v[70:71], v[70:71], v[70:71] op_sel:[0,1] op_sel_hi:[1,0]
	v_pk_add_f32 v[64:65], v[64:65], v[66:67]
	v_mov_b32_e32 v71, v1
	v_pk_add_f32 v[64:65], v[64:65], v[64:65] op_sel:[0,1] op_sel_hi:[1,0]
	s_nop 0
	v_mov_b32_e32 v65, v0
	v_pk_add_f32 v[64:65], v[64:65], v[70:71]
	s_nop 0
	v_pk_add_f32 v[64:65], v[64:65], v[72:73]
	s_nop 0
	v_add_f32_e32 v64, v64, v65
	ds_bpermute_b32 v65, v56, v64
	s_waitcnt lgkmcnt(0)
	v_add_f32_e32 v64, v64, v65
	ds_bpermute_b32 v65, v57, v64
	s_waitcnt lgkmcnt(0)
	v_add_f32_e32 v64, v64, v65
	ds_bpermute_b32 v65, v58, v64
	s_waitcnt lgkmcnt(0)
	v_add_f32_e32 v64, v64, v65
	ds_bpermute_b32 v65, v59, v64
	s_waitcnt lgkmcnt(0)
	v_add_f32_e32 v64, v64, v65
	ds_bpermute_b32 v65, v60, v64
	s_waitcnt lgkmcnt(0)
	v_add_f32_e32 v64, v64, v65
	ds_bpermute_b32 v65, v61, v64
	s_waitcnt lgkmcnt(0)
; __device__ __forceinline__ void ln_row(const float* xin, float* yout, bf16_t* ybf, const float* g, const float* b, int lane) {
;     ...
; #pragma unroll
;     for (int j = 0; j < 8; ++j) { v[j] = v[j] - mean; s2 += (v[j][0] * v[j][0] + v[j][1] * v[j][1]) + (v[j][2] * v[j][2] + v[j][3] * v[j][3]); }
;     const float rstd = 1.f / sqrtf(wave_sum(s2, lane) * (1.f / DM) + LN_EPS);
	v_add_f32_e32 v87, v64, v65
	v_fmamk_f32 v31, v87, 0xba000000, v31
	v_fmamk_f32 v29, v87, 0xba000000, v29
	v_fmamk_f32 v27, v87, 0xba000000, v27
	v_fmamk_f32 v25, v87, 0xba000000, v25
	v_fmamk_f32 v30, v87, 0xba000000, v30
	v_fmac_f32_e32 v28, 0xba000000, v87
	v_fmamk_f32 v26, v87, 0xba000000, v26
	v_fmac_f32_e32 v24, 0xba000000, v87
	v_fmamk_f32 v21, v87, 0xba000000, v21
	v_fmamk_f32 v20, v87, 0xba000000, v20
	v_fmamk_f32 v23, v87, 0xba000000, v23
	v_fmac_f32_e32 v22, 0xba000000, v87
	v_mov_b32_e32 v66, v29
	v_mov_b32_e32 v67, v25
	v_mov_b32_e32 v70, v31
	v_mov_b32_e32 v71, v27
	v_mov_b32_e32 v64, v28
	v_mov_b32_e32 v65, v24
	v_mov_b32_e32 v68, v30
	v_mov_b32_e32 v69, v26
	v_pk_mul_f32 v[72:73], v[22:23], v[22:23]
	v_pk_mul_f32 v[74:75], v[20:21], v[20:21]
	v_pk_mul_f32 v[66:67], v[66:67], v[66:67]
	v_pk_mul_f32 v[70:71], v[70:71], v[70:71]
	v_fmamk_f32 v16, v87, 0xba000000, v16
	v_fmac_f32_e32 v18, 0xba000000, v87
	v_pk_mov_b32 v[88:89], v[74:75], v[72:73] op_sel:[1,0]
	v_mov_b32_e32 v75, v73
	v_pk_fma_f32 v[64:65], v[64:65], v[64:65], v[66:67]
	v_pk_fma_f32 v[66:67], v[68:69], v[68:69], v[70:71]
	v_fmamk_f32 v17, v87, 0xba000000, v17
	v_fmamk_f32 v19, v87, 0xba000000, v19
	v_mul_f32_e32 v76, v16, v16
	v_mul_f32_e32 v78, v18, v18
	v_pk_add_f32 v[68:69], v[88:89], v[74:75]
	v_pk_add_f32 v[64:65], v[64:65], v[66:67]
	v_fmamk_f32 v11, v87, 0xba000000, v11
	v_fmamk_f32 v10, v87, 0xba000000, v10
	v_fmamk_f32 v9, v87, 0xba000000, v9
	v_fmac_f32_e32 v8, 0xba000000, v87
	v_fmamk_f32 v13, v87, 0xba000000, v13
	v_fmamk_f32 v12, v87, 0xba000000, v12
	v_fmamk_f32 v15, v87, 0xba000000, v15
	v_fmac_f32_e32 v14, 0xba000000, v87
	v_pk_fma_f32 v[72:73], v[16:17], v[16:17], v[76:77] op_sel_hi:[1,1,0]
	v_pk_fma_f32 v[76:77], v[18:19], v[18:19], v[78:79] op_sel_hi:[1,1,0]
	v_pk_add_f32 v[66:67], v[68:69], v[68:69] op_sel_hi:[0,1]
	v_pk_add_f32 v[64:65], v[64:65], v[64:65] op_sel_hi:[0,1]
	v_pk_mul_f32 v[80:81], v[14:15], v[14:15]
	v_pk_mul_f32 v[82:83], v[12:13], v[12:13]
	v_mul_f32_e32 v72, v8, v8
	v_mul_f32_e32 v76, v9, v9
	v_mul_f32_e32 v66, v10, v10
	v_mul_f32_e32 v64, v11, v11
	v_pk_mov_b32 v[78:79], v[82:83], v[80:81] op_sel:[1,0]
	v_mov_b32_e32 v83, v81
	v_pk_add_f32 v[68:69], v[72:73], v[76:77]
	v_pk_add_f32 v[64:65], v[66:67], v[64:65]
	v_pk_add_f32 v[70:71], v[78:79], v[82:83]
	v_pk_add_f32 v[64:65], v[68:69], v[64:65]
	v_pk_add_f32 v[72:73], v[70:71], v[70:71] op_sel_hi:[0,1]
	v_pk_add_f32 v[74:75], v[64:65], v[64:65] op_sel_hi:[0,1]
	v_fmamk_f32 v4, v87, 0xba000000, v4
	v_fmac_f32_e32 v6, 0xba000000, v87
	v_fmamk_f32 v5, v87, 0xba000000, v5
	v_fmamk_f32 v7, v87, 0xba000000, v7
	v_mul_f32_e32 v84, v4, v4
	v_mul_f32_e32 v86, v6, v6
	v_pk_fma_f32 v[80:81], v[4:5], v[4:5], v[84:85] op_sel_hi:[1, 1, 0]
	v_pk_fma_f32 v[84:85], v[6:7], v[6:7], v[86:87] op_sel_hi:[1, 1, 0]
	v_fmamk_f32 v77, v87, 0xba000000, v3
	v_fmamk_f32 v76, v87, 0xba000000, v2
	v_fmamk_f32 v1, v87, 0xba000000, v1
	v_fmac_f32_e32 v0, 0xba000000, v87
	v_mul_f32_e32 v80, v0, v0
	v_mul_f32_e32 v84, v1, v1
	v_mul_f32_e32 v72, v76, v76
	v_mul_f32_e32 v74, v77, v77
	v_pk_add_f32 v[2:3], v[80:81], v[84:85]
	v_pk_add_f32 v[72:73], v[72:73], v[74:75]
	s_nop 0
	v_pk_add_f32 v[2:3], v[2:3], v[72:73]
	s_nop 0
	v_add_f32_e32 v2, v2, v3
	ds_bpermute_b32 v3, v56, v2
	s_waitcnt lgkmcnt(0)
	v_add_f32_e32 v2, v2, v3
	ds_bpermute_b32 v3, v57, v2
	s_waitcnt lgkmcnt(0)
	v_add_f32_e32 v2, v2, v3
	ds_bpermute_b32 v3, v58, v2
	s_waitcnt lgkmcnt(0)
	v_add_f32_e32 v2, v2, v3
	ds_bpermute_b32 v3, v59, v2
	s_waitcnt lgkmcnt(0)
	v_add_f32_e32 v2, v2, v3
	ds_bpermute_b32 v3, v60, v2
	s_waitcnt lgkmcnt(0)
; __device__ __forceinline__ unsigned pk2(float lo, float hi) { return f2bf(lo) | (f2bf(hi) << 16); }
; __device__ __forceinline__ void ln_row(const float* xin, float* yout, bf16_t* ybf, const float* g, const float* b, int lane) {
;     ...
;     const float rstd = 1.f / sqrtf(wave_sum(s2, lane) * (1.f / DM) + LN_EPS);
;     f32x4* yo = (f32x4*)yout + lane; u32x2* o8 = (u32x2*)ybf + lane;
; #pragma unroll
;     for (int j = 0; j < 8; ++j) { const f32x4 gg = ((const f32x4*)g)[lane + 64 * j], bb = ((const f32x4*)b)[lane + 64 * j];
;         const f32x4 y = v[j] * rstd * gg + bb; yo[64 * j] = y; if (ybf) { u32x2 w; w.x = pk2(y[0], y[1]); w.y = pk2(y[2], y[3]); o8[64 * j] = w; } }
	v_add_f32_e32 v2, v2, v3
	ds_bpermute_b32 v3, v61, v2
	s_waitcnt lgkmcnt(0)
	v_add_f32_e32 v2, v2, v3
	v_fmamk_f32 v2, v2, 0x3a000000, v62
	v_mul_f32_e32 v3, 0x4f800000, v2
	v_cmp_gt_f32_e32 vcc, s5, v2
	s_nop 1
	v_cndmask_b32_e32 v2, v2, v3, vcc
	v_sqrt_f32_e32 v3, v2
	s_nop 0
	v_add_u32_e32 v72, -1, v3
	v_add_u32_e32 v73, 1, v3
	v_fma_f32 v74, -v72, v3, v2
	v_fma_f32 v75, -v73, v3, v2
	v_cmp_ge_f32_e64 s[0:1], 0, v74
	s_nop 1
	v_cndmask_b32_e64 v3, v3, v72, s[0:1]
	v_cmp_lt_f32_e64 s[0:1], 0, v75
	s_nop 1
	v_cndmask_b32_e64 v3, v3, v73, s[0:1]
	v_mul_f32_e32 v72, 0x37800000, v3
	v_cndmask_b32_e32 v3, v3, v72, vcc
	v_cmp_class_f32_e32 vcc, v2, v63
	s_nop 1
	v_cndmask_b32_e32 v2, v3, v2, vcc
	v_div_scale_f32 v3, s[0:1], v2, v2, 1.0
	v_rcp_f32_e32 v72, v3
	v_div_scale_f32 v73, vcc, 1.0, v2, 1.0
	v_fma_f32 v74, -v3, v72, 1.0
	v_fmac_f32_e32 v72, v74, v72
	v_mul_f32_e32 v74, v73, v72
	v_fma_f32 v75, -v3, v74, v73
	v_fmac_f32_e32 v74, v75, v72
	v_fma_f32 v3, -v3, v74, v73
	v_div_fmas_f32 v3, v3, v72, v74
	v_div_fixup_f32 v72, v3, v2, 1.0
	v_pk_mul_f32 v[2:3], v[28:29], v[72:73] op_sel_hi:[1, 0]
	v_pk_mul_f32 v[28:29], v[30:31], v[72:73] op_sel_hi:[1, 0]
	v_pk_mul_f32 v[24:25], v[24:25], v[72:73] op_sel_hi:[1, 0]
	v_pk_fma_f32 v[30:31], v[102:103], v[28:29], v[134:135]
	v_pk_fma_f32 v[28:29], v[100:101], v[2:3], v[132:133]
	global_store_dwordx4 v[54:55], v[28:31], off offset:-3072
	s_nop 1
	s_nop 0
	v_pk_mul_f32 v[2:3], v[26:27], v[72:73] op_sel_hi:[1, 0]
	v_pk_mul_f32 v[20:21], v[20:21], v[72:73] op_sel_hi:[1, 0]
	v_pk_mul_f32 v[16:17], v[16:17], v[72:73] op_sel_hi:[1, 0]
	v_pk_mul_f32 v[8:9], v[8:9], v[72:73] op_sel_hi:[1, 0]
	v_pk_mul_f32 v[12:13], v[12:13], v[72:73] op_sel_hi:[1, 0]
	v_pk_mul_f32 v[6:7], v[6:7], v[72:73] op_sel_hi:[1, 0]
	v_pk_mul_f32 v[0:1], v[0:1], v[72:73] op_sel_hi:[1, 0]
	v_pk_fma_f32 v[24:25], v[104:105], v[24:25], v[136:137]
	v_pk_fma_f32 v[26:27], v[106:107], v[2:3], v[138:139]
	global_store_dwordx4 v[54:55], v[24:27], off offset:-2048
	s_nop 1
	s_nop 0
	v_pk_mul_f32 v[2:3], v[22:23], v[72:73] op_sel_hi:[1, 0]
	v_pk_fma_f32 v[20:21], v[108:109], v[20:21], v[140:141]
	v_pk_fma_f32 v[22:23], v[110:111], v[2:3], v[142:143]
	global_store_dwordx4 v[54:55], v[20:23], off offset:-1024
	s_nop 1
	s_nop 0
	v_pk_mul_f32 v[2:3], v[18:19], v[72:73] op_sel_hi:[1, 0]
	v_pk_fma_f32 v[16:17], v[112:113], v[16:17], v[144:145]
	v_pk_fma_f32 v[18:19], v[114:115], v[2:3], v[146:147]
	global_store_dwordx4 v[52:53], v[16:19], off offset:-4096
	s_nop 1
	s_nop 0
	v_pk_mul_f32 v[2:3], v[10:11], v[72:73] op_sel_hi:[1, 0]
	v_pk_fma_f32 v[8:9], v[116:117], v[8:9], v[148:149]
	v_pk_fma_f32 v[10:11], v[118:119], v[2:3], v[150:151]
	global_store_dwordx4 v[52:53], v[8:11], off offset:-3072
	s_nop 1
	s_nop 0
	v_pk_mul_f32 v[2:3], v[14:15], v[72:73] op_sel_hi:[1, 0]
	v_pk_fma_f32 v[8:9], v[120:121], v[12:13], v[152:153]
	v_pk_fma_f32 v[10:11], v[122:123], v[2:3], v[154:155]
	global_store_dwordx4 v[52:53], v[8:11], off offset:-2048
	s_nop 1
	s_nop 0
	v_pk_mul_f32 v[2:3], v[4:5], v[72:73] op_sel_hi:[1, 0]
	v_pk_fma_f32 v[4:5], v[126:127], v[6:7], v[158:159]
	v_pk_fma_f32 v[2:3], v[124:125], v[2:3], v[156:157]
	global_store_dwordx4 v[52:53], v[2:5], off offset:-1024
	s_nop 1
	s_nop 0
	v_pk_mul_f32 v[10:11], v[76:77], v[72:73] op_sel_hi:[1, 0]
	v_pk_fma_f32 v[0:1], v[128:129], v[0:1], v[160:161]
	v_pk_fma_f32 v[2:3], v[130:131], v[10:11], v[162:163]
	global_store_dwordx4 v[52:53], v[0:3], off
	s_nop 1
	v_lshl_add_u64 v[52:53], v[52:53], 0, s[2:3]
	s_cbranch_scc0 .LBB0_1298
